# GEMM epilogue stores (GU/IN/RES) marked sc1 write-through to lighten the grid-barrier L2 writeback
# speedup vs baseline: 1.0121x; 1.0121x over previous
; __device__ __forceinline__ unsigned pk2(float lo, float hi) { unsigned r; asm volatile("v_cvt_pk_bf16_f32 %0, %1, %2" : "=v"(r) : "v"(lo), "v"(hi)); return r; }
;     __device__ __forceinline__ void operator()(const f32x4 (&acc)[2][2][4][2], const pg8::Unit& u, int wr, int wc, int fr, int fq) const {
;     ...
;         const int row0 = u.pm * 256 + wr * 64 + fr, cx = wc * 32 + 8 * fq;
;         f32x4 bv[2][2];
; #pragma unroll
;         for (int bj = 0; bj < 2; ++bj)
; #pragma unroll
;             for (int n = 0; n < 2; ++n) bv[bj][n] = *(const f32x4*)(bias + u.pn * 256 + bj * 128 + cx + 4 * n);
; #pragma unroll
;         for (int ai = 0; ai < 2; ++ai)
; #pragma unroll
;             for (int m = 0; m < 4; ++m) {
;                 bf16_t* rowp = base + (size_t)(row0 + ai * 128 + m * 16) * ld + ct + cx;
; #pragma unroll
;                 for (int bj = 0; bj < 2; ++bj) {
;                     const f32x4 v0 = acc[ai][bj][m][0] + bv[bj][0], v1 = acc[ai][bj][m][1] + bv[bj][1];
;                     u32x4 w; w.x = pk2(v0[0], v0[1]); w.y = pk2(v0[2], v0[3]); w.z = pk2(v1[0], v1[1]); w.w = pk2(v1[2], v1[3]);
;                     *(u32x4*)(rowp + bj * 128) = w;
.LBB0_585:
	s_ashr_i32 s57, s56, 31
	v_lshl_add_u64 v[134:135], s[56:57], 2, v[172:173]
	global_load_dwordx4 v[138:141], v[134:135], off offset:16
	global_load_dwordx4 v[142:145], v[134:135], off
	global_load_dwordx4 v[130:133], v[134:135], off offset:528
	s_nop 0
	global_load_dwordx4 v[134:137], v[134:135], off offset:512
	s_ashr_i32 s35, s34, 31
	s_lshl_b64 s[2:3], s[34:35], 1
	s_add_u32 s2, s54, s2
	v_lshl_add_u32 v150, s84, 8, v201
	s_addc_u32 s3, s55, s3
	v_lshlrev_b32_e32 v64, 1, v170
	v_lshl_add_u64 v[146:147], s[2:3], 0, v[64:65]
	v_ashrrev_i32_e32 v64, 31, v150
	v_mul_lo_u32 v64, s4, v64
	v_mul_lo_u32 v151, s5, v150
	v_mad_u64_u32 v[148:149], s[2:3], s4, v150, 0
	v_add3_u32 v149, v149, v64, v151
	v_lshl_add_u64 v[148:149], v[148:149], 1, v[146:147]
	s_waitcnt vmcnt(0)
	v_pk_add_f32 v[156:157], v[124:125], v[140:141]
	v_pk_add_f32 v[154:155], v[128:129], v[144:145]
	v_pk_add_f32 v[152:153], v[126:127], v[142:143]
	v_pk_add_f32 v[158:159], v[122:123], v[138:139]
	v_cvt_pk_bf16_f32 v152, v152, v153
	v_cvt_pk_bf16_f32 v153, v154, v155
	s_nop 0
	v_cvt_pk_bf16_f32 v154, v158, v159
	v_cvt_pk_bf16_f32 v155, v156, v157
	global_store_dwordx4 v[148:149], v[152:155], off sc1
	v_pk_add_f32 v[156:157], v[116:117], v[132:133]
	v_pk_add_f32 v[158:159], v[114:115], v[130:131]
	v_pk_add_f32 v[154:155], v[120:121], v[136:137]
	v_pk_add_f32 v[152:153], v[118:119], v[134:135]
	s_nop 0
	v_cvt_pk_bf16_f32 v152, v152, v153
	v_cvt_pk_bf16_f32 v153, v154, v155
	v_cvt_pk_bf16_f32 v154, v158, v159
	v_cvt_pk_bf16_f32 v155, v156, v157
	global_store_dwordx4 v[148:149], v[152:155], off offset:256 sc1
	v_or_b32_e32 v148, 16, v150
	v_mul_lo_u32 v151, s5, v148
	v_mad_u64_u32 v[148:149], s[2:3], s4, v148, 0
	v_add3_u32 v149, v149, v64, v151
	v_pk_add_f32 v[154:155], v[112:113], v[144:145]
	v_pk_add_f32 v[152:153], v[110:111], v[142:143]
	v_lshl_add_u64 v[148:149], v[148:149], 1, v[146:147]
	v_pk_add_f32 v[156:157], v[108:109], v[140:141]
	v_pk_add_f32 v[158:159], v[106:107], v[138:139]
	v_cvt_pk_bf16_f32 v152, v152, v153
	v_cvt_pk_bf16_f32 v153, v154, v155
	s_nop 0
	v_cvt_pk_bf16_f32 v154, v158, v159
	v_cvt_pk_bf16_f32 v155, v156, v157
	global_store_dwordx4 v[148:149], v[152:155], off sc1
	v_pk_add_f32 v[156:157], v[100:101], v[132:133]
	v_pk_add_f32 v[158:159], v[98:99], v[130:131]
	v_pk_add_f32 v[154:155], v[104:105], v[136:137]
	v_pk_add_f32 v[152:153], v[102:103], v[134:135]
	s_nop 0
	v_cvt_pk_bf16_f32 v152, v152, v153
	v_cvt_pk_bf16_f32 v153, v154, v155
	v_cvt_pk_bf16_f32 v154, v158, v159
	v_cvt_pk_bf16_f32 v155, v156, v157
	global_store_dwordx4 v[148:149], v[152:155], off offset:256 sc1
	v_or_b32_e32 v148, 32, v150
	v_mul_lo_u32 v151, s5, v148
	v_mad_u64_u32 v[148:149], s[2:3], s4, v148, 0
	v_add3_u32 v149, v149, v64, v151
	v_pk_add_f32 v[154:155], v[96:97], v[144:145]
	v_pk_add_f32 v[152:153], v[94:95], v[142:143]
	v_lshl_add_u64 v[148:149], v[148:149], 1, v[146:147]
	v_pk_add_f32 v[156:157], v[92:93], v[140:141]
	v_pk_add_f32 v[158:159], v[90:91], v[138:139]
	v_cvt_pk_bf16_f32 v152, v152, v153
	v_cvt_pk_bf16_f32 v153, v154, v155
	s_nop 0
	v_cvt_pk_bf16_f32 v154, v158, v159
	v_cvt_pk_bf16_f32 v155, v156, v157
	global_store_dwordx4 v[148:149], v[152:155], off sc1
	v_pk_add_f32 v[156:157], v[80:81], v[132:133]
	v_pk_add_f32 v[158:159], v[78:79], v[130:131]
	v_pk_add_f32 v[154:155], v[88:89], v[136:137]
	v_pk_add_f32 v[152:153], v[86:87], v[134:135]
	s_nop 0
	v_cvt_pk_bf16_f32 v152, v152, v153
	v_cvt_pk_bf16_f32 v153, v154, v155
	v_cvt_pk_bf16_f32 v154, v158, v159
	v_cvt_pk_bf16_f32 v155, v156, v157
	global_store_dwordx4 v[148:149], v[152:155], off offset:256 sc1
	v_or_b32_e32 v148, 48, v150
	v_mul_lo_u32 v151, s5, v148
	v_mad_u64_u32 v[148:149], s[2:3], s4, v148, 0
	v_add3_u32 v149, v149, v64, v151
	v_pk_add_f32 v[154:155], v[84:85], v[144:145]
	v_pk_add_f32 v[152:153], v[82:83], v[142:143]
	v_lshl_add_u64 v[148:149], v[148:149], 1, v[146:147]
	v_pk_add_f32 v[156:157], v[76:77], v[140:141]
	v_pk_add_f32 v[158:159], v[74:75], v[138:139]
	v_cvt_pk_bf16_f32 v152, v152, v153
	v_cvt_pk_bf16_f32 v153, v154, v155
	v_add_u32_e32 v64, 0x80, v150
	v_cvt_pk_bf16_f32 v154, v158, v159
	v_cvt_pk_bf16_f32 v155, v156, v157
	global_store_dwordx4 v[148:149], v[152:155], off sc1
	v_pk_add_f32 v[156:157], v[68:69], v[132:133]
	v_pk_add_f32 v[158:159], v[66:67], v[130:131]
	v_pk_add_f32 v[154:155], v[72:73], v[136:137]
	v_pk_add_f32 v[152:153], v[70:71], v[134:135]
; __device__ __forceinline__ unsigned pk2(float lo, float hi) { unsigned r; asm volatile("v_cvt_pk_bf16_f32 %0, %1, %2" : "=v"(r) : "v"(lo), "v"(hi)); return r; }
;     __device__ __forceinline__ void operator()(const f32x4 (&acc)[2][2][4][2], const pg8::Unit& u, int wr, int wc, int fr, int fq) const {
;     ...
; #pragma unroll
;         for (int ai = 0; ai < 2; ++ai)
; #pragma unroll
;             for (int m = 0; m < 4; ++m) {
;                 bf16_t* rowp = base + (size_t)(row0 + ai * 128 + m * 16) * ld + ct + cx;
; #pragma unroll
;                 for (int bj = 0; bj < 2; ++bj) {
;                     const f32x4 v0 = acc[ai][bj][m][0] + bv[bj][0], v1 = acc[ai][bj][m][1] + bv[bj][1];
;                     u32x4 w; w.x = pk2(v0[0], v0[1]); w.y = pk2(v0[2], v0[3]); w.z = pk2(v1[0], v1[1]); w.w = pk2(v1[2], v1[3]);
;                     *(u32x4*)(rowp + bj * 128) = w;
;                 }
	s_nop 0
	v_cvt_pk_bf16_f32 v152, v152, v153
	v_cvt_pk_bf16_f32 v153, v154, v155
	v_cvt_pk_bf16_f32 v154, v158, v159
	v_cvt_pk_bf16_f32 v155, v156, v157
	global_store_dwordx4 v[148:149], v[152:155], off offset:256 sc1
	v_ashrrev_i32_e32 v148, 31, v64
	v_mul_lo_u32 v151, s4, v148
	v_mul_lo_u32 v152, s5, v64
	v_mad_u64_u32 v[148:149], s[2:3], s4, v64, 0
	v_add3_u32 v149, v149, v151, v152
	v_pk_add_f32 v[154:155], v[62:63], v[144:145]
	v_pk_add_f32 v[152:153], v[60:61], v[142:143]
	v_lshl_add_u64 v[148:149], v[148:149], 1, v[146:147]
	v_pk_add_f32 v[156:157], v[58:59], v[140:141]
	v_pk_add_f32 v[158:159], v[56:57], v[138:139]
	v_cvt_pk_bf16_f32 v152, v152, v153
	v_cvt_pk_bf16_f32 v153, v154, v155
	v_add_u32_e32 v64, 0x90, v150
	v_cvt_pk_bf16_f32 v154, v158, v159
	v_cvt_pk_bf16_f32 v155, v156, v157
	global_store_dwordx4 v[148:149], v[152:155], off sc1
	v_pk_add_f32 v[156:157], v[50:51], v[132:133]
	v_pk_add_f32 v[158:159], v[48:49], v[130:131]
	v_pk_add_f32 v[154:155], v[54:55], v[136:137]
	v_pk_add_f32 v[152:153], v[52:53], v[134:135]
	s_nop 0
	v_cvt_pk_bf16_f32 v152, v152, v153
	v_cvt_pk_bf16_f32 v153, v154, v155
	v_cvt_pk_bf16_f32 v154, v158, v159
	v_cvt_pk_bf16_f32 v155, v156, v157
	global_store_dwordx4 v[148:149], v[152:155], off offset:256 sc1
	v_ashrrev_i32_e32 v148, 31, v64
	v_mul_lo_u32 v151, s4, v148
	v_mul_lo_u32 v152, s5, v64
	v_mad_u64_u32 v[148:149], s[2:3], s4, v64, 0
	v_add3_u32 v149, v149, v151, v152
	v_pk_add_f32 v[154:155], v[46:47], v[144:145]
	v_pk_add_f32 v[152:153], v[44:45], v[142:143]
	v_lshl_add_u64 v[148:149], v[148:149], 1, v[146:147]
	v_pk_add_f32 v[156:157], v[42:43], v[140:141]
	v_pk_add_f32 v[158:159], v[40:41], v[138:139]
	v_cvt_pk_bf16_f32 v152, v152, v153
	v_cvt_pk_bf16_f32 v153, v154, v155
	v_add_u32_e32 v64, 0xa0, v150
	v_cvt_pk_bf16_f32 v154, v158, v159
	v_cvt_pk_bf16_f32 v155, v156, v157
	global_store_dwordx4 v[148:149], v[152:155], off sc1
	v_pk_add_f32 v[156:157], v[34:35], v[132:133]
	v_pk_add_f32 v[158:159], v[32:33], v[130:131]
	v_pk_add_f32 v[154:155], v[38:39], v[136:137]
	v_pk_add_f32 v[152:153], v[36:37], v[134:135]
	s_nop 0
	v_cvt_pk_bf16_f32 v152, v152, v153
	v_cvt_pk_bf16_f32 v153, v154, v155
	v_cvt_pk_bf16_f32 v154, v158, v159
	v_cvt_pk_bf16_f32 v155, v156, v157
	global_store_dwordx4 v[148:149], v[152:155], off offset:256 sc1
	v_ashrrev_i32_e32 v148, 31, v64
	v_mul_lo_u32 v151, s4, v148
	v_mul_lo_u32 v152, s5, v64
	v_mad_u64_u32 v[148:149], s[2:3], s4, v64, 0
	v_add3_u32 v149, v149, v151, v152
	v_pk_add_f32 v[154:155], v[30:31], v[144:145]
	v_pk_add_f32 v[152:153], v[28:29], v[142:143]
	v_lshl_add_u64 v[148:149], v[148:149], 1, v[146:147]
	v_pk_add_f32 v[156:157], v[26:27], v[140:141]
	v_pk_add_f32 v[158:159], v[24:25], v[138:139]
	v_cvt_pk_bf16_f32 v152, v152, v153
	v_cvt_pk_bf16_f32 v153, v154, v155
	v_add_u32_e32 v64, 0xb0, v150
	v_cvt_pk_bf16_f32 v154, v158, v159
	v_cvt_pk_bf16_f32 v155, v156, v157
	global_store_dwordx4 v[148:149], v[152:155], off sc1
	v_pk_add_f32 v[156:157], v[14:15], v[132:133]
	v_pk_add_f32 v[158:159], v[12:13], v[130:131]
	v_pk_add_f32 v[154:155], v[18:19], v[136:137]
	v_pk_add_f32 v[152:153], v[16:17], v[134:135]
	v_mul_lo_u32 v151, s5, v64
	v_cvt_pk_bf16_f32 v152, v152, v153
	v_cvt_pk_bf16_f32 v153, v154, v155
	v_cvt_pk_bf16_f32 v154, v158, v159
	v_cvt_pk_bf16_f32 v155, v156, v157
	global_store_dwordx4 v[148:149], v[152:155], off offset:256 sc1
	v_ashrrev_i32_e32 v148, 31, v64
	v_mul_lo_u32 v150, s4, v148
	v_mad_u64_u32 v[148:149], s[2:3], s4, v64, 0
	v_add3_u32 v149, v149, v150, v151
	v_lshl_add_u64 v[146:147], v[148:149], 1, v[146:147]
	v_pk_add_f32 v[144:145], v[22:23], v[144:145]
	v_pk_add_f32 v[142:143], v[20:21], v[142:143]
	v_pk_add_f32 v[148:149], v[10:11], v[140:141]
	v_pk_add_f32 v[140:141], v[8:9], v[138:139]
	v_cvt_pk_bf16_f32 v138, v142, v143
	v_cvt_pk_bf16_f32 v139, v144, v145
	v_pk_add_f32 v[136:137], v[6:7], v[136:137]
	v_cvt_pk_bf16_f32 v140, v140, v141
	v_cvt_pk_bf16_f32 v141, v148, v149
	global_store_dwordx4 v[146:147], v[138:141], off sc1
	v_pk_add_f32 v[134:135], v[4:5], v[134:135]
	s_nop 0
	v_pk_add_f32 v[138:139], v[2:3], v[132:133]
	v_pk_add_f32 v[132:133], v[0:1], v[130:131]
	v_cvt_pk_bf16_f32 v130, v134, v135
	v_cvt_pk_bf16_f32 v131, v136, v137
	s_nop 0
	v_cvt_pk_bf16_f32 v132, v132, v133
	v_cvt_pk_bf16_f32 v133, v138, v139
	global_store_dwordx4 v[146:147], v[130:133], off offset:256 sc1

; __device__ __forceinline__ unsigned pk2(float lo, float hi) { unsigned r; asm volatile("v_cvt_pk_bf16_f32 %0, %1, %2" : "=v"(r) : "v"(lo), "v"(hi)); return r; }
; __device__ __forceinline__ float siluf_(float x) { return x * sigmoidf_(x); }
;     __device__ __forceinline__ void operator()(const f32x4 (&acc)[2][2][4][2], const pg8::Unit& u, int wr, int wc, int fr, int fq) const {
;         const int row0 = u.pm * 256 + wr * 64 + fr, col0 = u.pn * 128 + wc * 32 + 8 * fq;
; #pragma unroll
;         for (int ai = 0; ai < 2; ++ai)
; #pragma unroll
;             for (int m = 0; m < 4; ++m) {
;                 bf16_t* rowp = H + (size_t)(row0 + ai * 128 + m * 16) * F_ + col0;
;                 const f32x4 g0 = acc[ai][0][m][0], g1 = acc[ai][0][m][1], u0 = acc[ai][1][m][0], u1 = acc[ai][1][m][1];
;                 u32x4 w;
;                 w.x = pk2(siluf_(g0[0]) * u0[0], siluf_(g0[1]) * u0[1]); w.y = pk2(siluf_(g0[2]) * u0[2], siluf_(g0[3]) * u0[3]);
;                 w.z = pk2(siluf_(g1[0]) * u1[0], siluf_(g1[1]) * u1[1]); w.w = pk2(siluf_(g1[2]) * u1[2], siluf_(g1[3]) * u1[3]);
;                 *(u32x4*)rowp = w;
;             }
.LBB0_587:
	s_mov_b64 s[2:3], -1
	s_cmp_eq_u32 s58, 1
	v_lshl_add_u32 v130, s84, 8, v201
	s_cbranch_scc1 .LBB0_589
	v_mul_f32_e32 v64, 0xbfb8aa3b, v126
	v_exp_f32_e32 v64, v64
	v_mul_f32_e32 v131, 0xbfb8aa3b, v127
	v_exp_f32_e32 v131, v131
	v_readlane_b32 s2, v246, 17
	v_add_f32_e32 v64, 1.0, v64
	v_rcp_f32_e32 v64, v64
	v_add_f32_e32 v131, 1.0, v131
	v_rcp_f32_e32 v131, v131
	v_lshl_or_b32 v134, s83, 7, v170
	v_readlane_b32 s3, v246, 18
	v_ashrrev_i32_e32 v135, 31, v134
	s_movk_i32 s4, 0x2c00
	v_mov_b64_e32 v[132:133], s[2:3]
	v_mul_f32_e32 v64, v126, v64
	v_mad_i64_i32 v[136:137], s[2:3], v130, s4, v[132:133]
	v_lshlrev_b64 v[134:135], 1, v[134:135]
	v_mul_f32_e32 v64, v64, v118
	v_mul_f32_e32 v131, v127, v131
	v_lshl_add_u64 v[140:141], v[136:137], 0, v[134:135]
	v_mul_f32_e32 v131, v131, v119
	v_cvt_pk_bf16_f32 v136, v64, v131
	v_mul_f32_e32 v64, 0xbfb8aa3b, v128
	v_exp_f32_e32 v64, v64
	v_mul_f32_e32 v131, 0xbfb8aa3b, v129
	v_exp_f32_e32 v131, v131
	v_add_f32_e32 v64, 1.0, v64
	v_rcp_f32_e32 v64, v64
	v_add_f32_e32 v131, 1.0, v131
	v_rcp_f32_e32 v131, v131
	v_mul_f32_e32 v64, v128, v64
	v_mul_f32_e32 v64, v64, v120
	v_mul_f32_e32 v131, v129, v131
	v_mul_f32_e32 v131, v131, v121
	v_cvt_pk_bf16_f32 v137, v64, v131
	v_mul_f32_e32 v64, 0xbfb8aa3b, v122
	v_exp_f32_e32 v64, v64
	v_mul_f32_e32 v131, 0xbfb8aa3b, v123
	v_exp_f32_e32 v131, v131
	v_add_f32_e32 v64, 1.0, v64
	v_rcp_f32_e32 v64, v64
	v_add_f32_e32 v131, 1.0, v131
	v_rcp_f32_e32 v131, v131
	v_mul_f32_e32 v64, v122, v64
	v_mul_f32_e32 v64, v64, v114
	v_mul_f32_e32 v131, v123, v131
	v_mul_f32_e32 v131, v131, v115
	v_cvt_pk_bf16_f32 v138, v64, v131
	v_mul_f32_e32 v64, 0xbfb8aa3b, v124
	v_exp_f32_e32 v64, v64
	v_mul_f32_e32 v131, 0xbfb8aa3b, v125
	v_exp_f32_e32 v131, v131
	v_add_f32_e32 v64, 1.0, v64
	v_rcp_f32_e32 v64, v64
	v_add_f32_e32 v131, 1.0, v131
	v_rcp_f32_e32 v131, v131
	v_mul_f32_e32 v64, v124, v64
	v_mul_f32_e32 v64, v64, v116
	v_mul_f32_e32 v131, v125, v131
	v_mul_f32_e32 v131, v131, v117
	v_cvt_pk_bf16_f32 v139, v64, v131
	v_or_b32_e32 v64, 16, v130
	global_store_dwordx4 v[140:141], v[136:139], off sc1
	v_mul_f32_e32 v131, 0xbfb8aa3b, v111
	v_exp_f32_e32 v131, v131
	v_mad_i64_i32 v[136:137], s[2:3], v64, s4, v[132:133]
	v_mul_f32_e32 v64, 0xbfb8aa3b, v110
	v_exp_f32_e32 v64, v64
	v_add_f32_e32 v131, 1.0, v131
	v_rcp_f32_e32 v131, v131
	v_lshl_add_u64 v[140:141], v[136:137], 0, v[134:135]
	v_add_f32_e32 v64, 1.0, v64
	v_rcp_f32_e32 v64, v64
	v_mul_f32_e32 v131, v111, v131
	v_mul_f32_e32 v131, v131, v103
	v_mul_f32_e32 v64, v110, v64
	v_mul_f32_e32 v64, v64, v102
	v_cvt_pk_bf16_f32 v136, v64, v131
	v_mul_f32_e32 v64, 0xbfb8aa3b, v112
	v_exp_f32_e32 v64, v64
	v_mul_f32_e32 v131, 0xbfb8aa3b, v113
	v_exp_f32_e32 v131, v131
	v_add_f32_e32 v64, 1.0, v64
	v_rcp_f32_e32 v64, v64
	v_add_f32_e32 v131, 1.0, v131
	v_rcp_f32_e32 v131, v131
	v_mul_f32_e32 v64, v112, v64
	v_mul_f32_e32 v64, v64, v104
	v_mul_f32_e32 v131, v113, v131
	v_mul_f32_e32 v131, v131, v105
	v_cvt_pk_bf16_f32 v137, v64, v131
	v_mul_f32_e32 v64, 0xbfb8aa3b, v106
	v_exp_f32_e32 v64, v64
	v_mul_f32_e32 v131, 0xbfb8aa3b, v107
	v_exp_f32_e32 v131, v131
	v_add_f32_e32 v64, 1.0, v64
	v_rcp_f32_e32 v64, v64
	v_add_f32_e32 v131, 1.0, v131
	v_rcp_f32_e32 v131, v131
	v_mul_f32_e32 v64, v106, v64
	v_mul_f32_e32 v64, v64, v98
	v_mul_f32_e32 v131, v107, v131
	v_mul_f32_e32 v131, v131, v99
	v_cvt_pk_bf16_f32 v138, v64, v131
	v_mul_f32_e32 v64, 0xbfb8aa3b, v108
	v_exp_f32_e32 v64, v64
	v_mul_f32_e32 v131, 0xbfb8aa3b, v109
	v_exp_f32_e32 v131, v131
	v_add_f32_e32 v64, 1.0, v64
	v_rcp_f32_e32 v64, v64
	v_add_f32_e32 v131, 1.0, v131
	v_rcp_f32_e32 v131, v131
	v_mul_f32_e32 v64, v108, v64
	v_mul_f32_e32 v64, v64, v100
	v_mul_f32_e32 v131, v109, v131
	v_mul_f32_e32 v131, v131, v101
	v_cvt_pk_bf16_f32 v139, v64, v131
	v_or_b32_e32 v64, 32, v130
	global_store_dwordx4 v[140:141], v[136:139], off sc1
	v_mul_f32_e32 v131, 0xbfb8aa3b, v95
	v_exp_f32_e32 v131, v131
	v_mad_i64_i32 v[136:137], s[2:3], v64, s4, v[132:133]
	v_mul_f32_e32 v64, 0xbfb8aa3b, v94
	v_exp_f32_e32 v64, v64
	v_add_f32_e32 v131, 1.0, v131
	v_rcp_f32_e32 v131, v131
	v_lshl_add_u64 v[140:141], v[136:137], 0, v[134:135]
	v_add_f32_e32 v64, 1.0, v64
	v_rcp_f32_e32 v64, v64
	v_mul_f32_e32 v131, v95, v131
	v_mul_f32_e32 v131, v131, v87
	v_mul_f32_e32 v64, v94, v64
	v_mul_f32_e32 v64, v64, v86
	v_cvt_pk_bf16_f32 v136, v64, v131
	v_mul_f32_e32 v64, 0xbfb8aa3b, v96
	v_exp_f32_e32 v64, v64
	v_mul_f32_e32 v131, 0xbfb8aa3b, v97
	v_exp_f32_e32 v131, v131
	v_add_f32_e32 v64, 1.0, v64
	v_rcp_f32_e32 v64, v64
	v_add_f32_e32 v131, 1.0, v131
	v_rcp_f32_e32 v131, v131
	v_mul_f32_e32 v64, v96, v64
	v_mul_f32_e32 v64, v64, v88
	v_mul_f32_e32 v131, v97, v131
	v_mul_f32_e32 v131, v131, v89
	v_cvt_pk_bf16_f32 v137, v64, v131
	v_mul_f32_e32 v64, 0xbfb8aa3b, v90
	v_exp_f32_e32 v64, v64
	v_mul_f32_e32 v131, 0xbfb8aa3b, v91
	v_exp_f32_e32 v131, v131
	v_add_f32_e32 v64, 1.0, v64
	v_rcp_f32_e32 v64, v64
	v_add_f32_e32 v131, 1.0, v131
	v_rcp_f32_e32 v131, v131
	v_mul_f32_e32 v64, v90, v64
	v_mul_f32_e32 v64, v64, v78
	v_mul_f32_e32 v131, v91, v131
	v_mul_f32_e32 v131, v131, v79
	v_cvt_pk_bf16_f32 v138, v64, v131
	v_mul_f32_e32 v64, 0xbfb8aa3b, v92
	v_exp_f32_e32 v64, v64
	v_mul_f32_e32 v131, 0xbfb8aa3b, v93
	v_exp_f32_e32 v131, v131
	v_add_f32_e32 v64, 1.0, v64
	v_rcp_f32_e32 v64, v64
	v_add_f32_e32 v131, 1.0, v131
	v_rcp_f32_e32 v131, v131
	v_mul_f32_e32 v64, v92, v64
	v_mul_f32_e32 v64, v64, v80
	v_mul_f32_e32 v131, v93, v131
	v_mul_f32_e32 v131, v131, v81
	v_cvt_pk_bf16_f32 v139, v64, v131
	v_or_b32_e32 v64, 48, v130
	global_store_dwordx4 v[140:141], v[136:139], off sc1
	v_mul_f32_e32 v131, 0xbfb8aa3b, v83
; __device__ __forceinline__ unsigned pk2(float lo, float hi) { unsigned r; asm volatile("v_cvt_pk_bf16_f32 %0, %1, %2" : "=v"(r) : "v"(lo), "v"(hi)); return r; }
; __device__ __forceinline__ float siluf_(float x) { return x * sigmoidf_(x); }
;     __device__ __forceinline__ void operator()(const f32x4 (&acc)[2][2][4][2], const pg8::Unit& u, int wr, int wc, int fr, int fq) const {
;     ...
;             for (int m = 0; m < 4; ++m) {
;                 bf16_t* rowp = H + (size_t)(row0 + ai * 128 + m * 16) * F_ + col0;
;                 const f32x4 g0 = acc[ai][0][m][0], g1 = acc[ai][0][m][1], u0 = acc[ai][1][m][0], u1 = acc[ai][1][m][1];
;                 u32x4 w;
;                 w.x = pk2(siluf_(g0[0]) * u0[0], siluf_(g0[1]) * u0[1]); w.y = pk2(siluf_(g0[2]) * u0[2], siluf_(g0[3]) * u0[3]);
;                 w.z = pk2(siluf_(g1[0]) * u1[0], siluf_(g1[1]) * u1[1]); w.w = pk2(siluf_(g1[2]) * u1[2], siluf_(g1[3]) * u1[3]);
;                 *(u32x4*)rowp = w;
;             }
	v_exp_f32_e32 v131, v131
	v_mad_i64_i32 v[136:137], s[2:3], v64, s4, v[132:133]
	v_mul_f32_e32 v64, 0xbfb8aa3b, v82
	v_exp_f32_e32 v64, v64
	v_add_f32_e32 v131, 1.0, v131
	v_rcp_f32_e32 v131, v131
	v_lshl_add_u64 v[140:141], v[136:137], 0, v[134:135]
	v_add_f32_e32 v64, 1.0, v64
	v_rcp_f32_e32 v64, v64
	v_mul_f32_e32 v131, v83, v131
	v_mul_f32_e32 v131, v131, v71
	v_mul_f32_e32 v64, v82, v64
	v_mul_f32_e32 v64, v64, v70
	v_cvt_pk_bf16_f32 v136, v64, v131
	v_mul_f32_e32 v64, 0xbfb8aa3b, v84
	v_exp_f32_e32 v64, v64
	v_mul_f32_e32 v131, 0xbfb8aa3b, v85
	v_exp_f32_e32 v131, v131
	v_add_f32_e32 v64, 1.0, v64
	v_rcp_f32_e32 v64, v64
	v_add_f32_e32 v131, 1.0, v131
	v_rcp_f32_e32 v131, v131
	v_mul_f32_e32 v64, v84, v64
	v_mul_f32_e32 v64, v64, v72
	v_mul_f32_e32 v131, v85, v131
	v_mul_f32_e32 v131, v131, v73
	v_cvt_pk_bf16_f32 v137, v64, v131
	v_mul_f32_e32 v64, 0xbfb8aa3b, v74
	v_exp_f32_e32 v64, v64
	v_mul_f32_e32 v131, 0xbfb8aa3b, v75
	v_exp_f32_e32 v131, v131
	v_add_f32_e32 v64, 1.0, v64
	v_rcp_f32_e32 v64, v64
	v_add_f32_e32 v131, 1.0, v131
	v_rcp_f32_e32 v131, v131
	v_mul_f32_e32 v64, v74, v64
	v_mul_f32_e32 v64, v64, v66
	v_mul_f32_e32 v131, v75, v131
	v_mul_f32_e32 v131, v131, v67
	v_cvt_pk_bf16_f32 v138, v64, v131
	v_mul_f32_e32 v64, 0xbfb8aa3b, v76
	v_exp_f32_e32 v64, v64
	v_mul_f32_e32 v131, 0xbfb8aa3b, v77
	v_exp_f32_e32 v131, v131
	v_add_f32_e32 v64, 1.0, v64
	v_rcp_f32_e32 v64, v64
	v_add_f32_e32 v131, 1.0, v131
	v_rcp_f32_e32 v131, v131
	v_mul_f32_e32 v64, v76, v64
	v_mul_f32_e32 v64, v64, v68
	v_mul_f32_e32 v131, v77, v131
	v_mul_f32_e32 v131, v131, v69
	v_cvt_pk_bf16_f32 v139, v64, v131
	v_add_u32_e32 v64, 0x80, v130
	global_store_dwordx4 v[140:141], v[136:139], off sc1
	v_mul_f32_e32 v131, 0xbfb8aa3b, v61
	v_exp_f32_e32 v131, v131
	v_mad_i64_i32 v[136:137], s[2:3], v64, s4, v[132:133]
	v_mul_f32_e32 v64, 0xbfb8aa3b, v60
	v_exp_f32_e32 v64, v64
	v_add_f32_e32 v131, 1.0, v131
	v_rcp_f32_e32 v131, v131
	v_lshl_add_u64 v[140:141], v[136:137], 0, v[134:135]
	v_add_f32_e32 v64, 1.0, v64
	v_rcp_f32_e32 v64, v64
	v_mul_f32_e32 v131, v61, v131
	v_mul_f32_e32 v131, v131, v53
	v_mul_f32_e32 v64, v60, v64
	v_mul_f32_e32 v64, v64, v52
	v_cvt_pk_bf16_f32 v136, v64, v131
	v_mul_f32_e32 v64, 0xbfb8aa3b, v62
	v_exp_f32_e32 v64, v64
	v_mul_f32_e32 v131, 0xbfb8aa3b, v63
	v_exp_f32_e32 v131, v131
	v_add_f32_e32 v64, 1.0, v64
	v_rcp_f32_e32 v64, v64
	v_add_f32_e32 v131, 1.0, v131
	v_rcp_f32_e32 v131, v131
	v_mul_f32_e32 v64, v62, v64
	v_mul_f32_e32 v64, v64, v54
	v_mul_f32_e32 v131, v63, v131
	v_mul_f32_e32 v131, v131, v55
	v_cvt_pk_bf16_f32 v137, v64, v131
	v_mul_f32_e32 v64, 0xbfb8aa3b, v56
	v_exp_f32_e32 v64, v64
	v_mul_f32_e32 v131, 0xbfb8aa3b, v57
	v_exp_f32_e32 v131, v131
	v_add_f32_e32 v64, 1.0, v64
	v_rcp_f32_e32 v64, v64
	v_add_f32_e32 v131, 1.0, v131
	v_rcp_f32_e32 v131, v131
	v_mul_f32_e32 v64, v56, v64
	v_mul_f32_e32 v64, v64, v48
	v_mul_f32_e32 v131, v57, v131
	v_mul_f32_e32 v131, v131, v49
	v_cvt_pk_bf16_f32 v138, v64, v131
	v_mul_f32_e32 v64, 0xbfb8aa3b, v58
	v_exp_f32_e32 v64, v64
	v_mul_f32_e32 v131, 0xbfb8aa3b, v59
	v_exp_f32_e32 v131, v131
	v_add_f32_e32 v64, 1.0, v64
	v_rcp_f32_e32 v64, v64
	v_add_f32_e32 v131, 1.0, v131
	v_rcp_f32_e32 v131, v131
	v_mul_f32_e32 v64, v58, v64
	v_mul_f32_e32 v64, v64, v50
	v_mul_f32_e32 v131, v59, v131
	v_mul_f32_e32 v131, v131, v51
	v_cvt_pk_bf16_f32 v139, v64, v131
	v_add_u32_e32 v64, 0x90, v130
	global_store_dwordx4 v[140:141], v[136:139], off sc1
	v_mul_f32_e32 v131, 0xbfb8aa3b, v45
	v_exp_f32_e32 v131, v131
	v_mad_i64_i32 v[136:137], s[2:3], v64, s4, v[132:133]
	v_mul_f32_e32 v64, 0xbfb8aa3b, v44
	v_exp_f32_e32 v64, v64
	v_add_f32_e32 v131, 1.0, v131
	v_rcp_f32_e32 v131, v131
	v_lshl_add_u64 v[140:141], v[136:137], 0, v[134:135]
	v_add_f32_e32 v64, 1.0, v64
	v_rcp_f32_e32 v64, v64
	v_mul_f32_e32 v131, v45, v131
	v_mul_f32_e32 v131, v131, v37
	v_mul_f32_e32 v64, v44, v64
	v_mul_f32_e32 v64, v64, v36
	v_cvt_pk_bf16_f32 v136, v64, v131
	v_mul_f32_e32 v64, 0xbfb8aa3b, v46
	v_exp_f32_e32 v64, v64
	v_mul_f32_e32 v131, 0xbfb8aa3b, v47
	v_exp_f32_e32 v131, v131
	v_add_f32_e32 v64, 1.0, v64
	v_rcp_f32_e32 v64, v64
	v_add_f32_e32 v131, 1.0, v131
	v_rcp_f32_e32 v131, v131
	v_mul_f32_e32 v64, v46, v64
	v_mul_f32_e32 v64, v64, v38
	v_mul_f32_e32 v131, v47, v131
	v_mul_f32_e32 v131, v131, v39
	v_cvt_pk_bf16_f32 v137, v64, v131
	v_mul_f32_e32 v64, 0xbfb8aa3b, v40
	v_exp_f32_e32 v64, v64
	v_mul_f32_e32 v131, 0xbfb8aa3b, v41
	v_exp_f32_e32 v131, v131
	v_add_f32_e32 v64, 1.0, v64
	v_rcp_f32_e32 v64, v64
	v_add_f32_e32 v131, 1.0, v131
	v_rcp_f32_e32 v131, v131
	v_mul_f32_e32 v64, v40, v64
	v_mul_f32_e32 v64, v64, v32
	v_mul_f32_e32 v131, v41, v131
	v_mul_f32_e32 v131, v131, v33
	v_cvt_pk_bf16_f32 v138, v64, v131
	v_mul_f32_e32 v64, 0xbfb8aa3b, v42
	v_exp_f32_e32 v64, v64
	v_mul_f32_e32 v131, 0xbfb8aa3b, v43
	v_exp_f32_e32 v131, v131
	v_add_f32_e32 v64, 1.0, v64
	v_rcp_f32_e32 v64, v64
	v_add_f32_e32 v131, 1.0, v131
	v_rcp_f32_e32 v131, v131
	v_mul_f32_e32 v64, v42, v64
	v_mul_f32_e32 v64, v64, v34
	v_mul_f32_e32 v131, v43, v131
	v_mul_f32_e32 v131, v131, v35
	v_cvt_pk_bf16_f32 v139, v64, v131
	v_add_u32_e32 v64, 0xa0, v130
	global_store_dwordx4 v[140:141], v[136:139], off sc1
	v_mul_f32_e32 v131, 0xbfb8aa3b, v29
	v_exp_f32_e32 v131, v131
	v_mad_i64_i32 v[136:137], s[2:3], v64, s4, v[132:133]
	v_mul_f32_e32 v64, 0xbfb8aa3b, v28
	v_exp_f32_e32 v64, v64
	v_add_f32_e32 v131, 1.0, v131
	v_rcp_f32_e32 v131, v131
	v_lshl_add_u64 v[140:141], v[136:137], 0, v[134:135]
	v_add_f32_e32 v64, 1.0, v64
	v_rcp_f32_e32 v64, v64
	v_mul_f32_e32 v131, v29, v131
	v_mul_f32_e32 v131, v131, v17
	v_mul_f32_e32 v64, v28, v64
; __device__ __forceinline__ unsigned pk2(float lo, float hi) { unsigned r; asm volatile("v_cvt_pk_bf16_f32 %0, %1, %2" : "=v"(r) : "v"(lo), "v"(hi)); return r; }
; __device__ __forceinline__ float siluf_(float x) { return x * sigmoidf_(x); }
;     __device__ __forceinline__ void operator()(const f32x4 (&acc)[2][2][4][2], const pg8::Unit& u, int wr, int wc, int fr, int fq) const {
;     ...
;                 bf16_t* rowp = H + (size_t)(row0 + ai * 128 + m * 16) * F_ + col0;
;                 const f32x4 g0 = acc[ai][0][m][0], g1 = acc[ai][0][m][1], u0 = acc[ai][1][m][0], u1 = acc[ai][1][m][1];
;                 u32x4 w;
;                 w.x = pk2(siluf_(g0[0]) * u0[0], siluf_(g0[1]) * u0[1]); w.y = pk2(siluf_(g0[2]) * u0[2], siluf_(g0[3]) * u0[3]);
;                 w.z = pk2(siluf_(g1[0]) * u1[0], siluf_(g1[1]) * u1[1]); w.w = pk2(siluf_(g1[2]) * u1[2], siluf_(g1[3]) * u1[3]);
;                 *(u32x4*)rowp = w;
;             }
;     __device__ __forceinline__ void operator()(const f32x4 (&acc)[2][2][4][2], const pg8::Unit& u, int wr, int wc, int fr, int fq) const {
;         const int row0 = u.pm * 256 + wr * 64 + fr, col0 = u.pn * 256 + wc * 32 + 4 * fq;
;         f32x4 cur[4], nxt[4];
;         {   const size_t off = (size_t)row0 * D_ + col0;
; #pragma unroll
;             for (int j = 0; j < 4; ++j) cur[j] = *(const f32x4*)(res + off + (j >> 1) * 128 + (j & 1) * 16); }
; #pragma unroll
;         for (int g = 0; g < 8; ++g) {
;             const int ai = g >> 2, m = g & 3;
;             if (g < 7) { const int ai2 = (g + 1) >> 2, m2 = (g + 1) & 3; const size_t off2 = (size_t)(row0 + ai2 * 128 + m2 * 16) * D_ + col0;
; #pragma unroll
;                 for (int j = 0; j < 4; ++j) nxt[j] = *(const f32x4*)(res + off2 + (j >> 1) * 128 + (j & 1) * 16); }
;             const size_t off = (size_t)(row0 + ai * 128 + m * 16) * D_ + col0;
; #pragma unroll
;             for (int j = 0; j < 4; ++j) *(f32x4*)(out + off + (j >> 1) * 128 + (j & 1) * 16) = cur[j] + scale * acc[ai][j >> 1][m][j & 1];
	v_mul_f32_e32 v64, v64, v16
	v_cvt_pk_bf16_f32 v136, v64, v131
	v_mul_f32_e32 v64, 0xbfb8aa3b, v30
	v_exp_f32_e32 v64, v64
	v_mul_f32_e32 v131, 0xbfb8aa3b, v31
	v_exp_f32_e32 v131, v131
	v_add_f32_e32 v64, 1.0, v64
	v_rcp_f32_e32 v64, v64
	v_add_f32_e32 v131, 1.0, v131
	v_rcp_f32_e32 v131, v131
	v_mul_f32_e32 v64, v30, v64
	v_mul_f32_e32 v64, v64, v18
	v_mul_f32_e32 v131, v31, v131
	v_mul_f32_e32 v131, v131, v19
	v_cvt_pk_bf16_f32 v137, v64, v131
	v_mul_f32_e32 v64, 0xbfb8aa3b, v24
	v_exp_f32_e32 v64, v64
	v_mul_f32_e32 v131, 0xbfb8aa3b, v25
	v_exp_f32_e32 v131, v131
	v_add_f32_e32 v64, 1.0, v64
	v_rcp_f32_e32 v64, v64
	v_add_f32_e32 v131, 1.0, v131
	v_rcp_f32_e32 v131, v131
	v_mul_f32_e32 v64, v24, v64
	v_mul_f32_e32 v64, v64, v12
	v_mul_f32_e32 v131, v25, v131
	v_mul_f32_e32 v131, v131, v13
	v_cvt_pk_bf16_f32 v138, v64, v131
	v_mul_f32_e32 v64, 0xbfb8aa3b, v26
	v_exp_f32_e32 v64, v64
	v_mul_f32_e32 v131, 0xbfb8aa3b, v27
	v_exp_f32_e32 v131, v131
	v_add_f32_e32 v64, 1.0, v64
	v_rcp_f32_e32 v64, v64
	v_add_f32_e32 v131, 1.0, v131
	v_rcp_f32_e32 v131, v131
	v_mul_f32_e32 v64, v26, v64
	v_mul_f32_e32 v64, v64, v14
	v_mul_f32_e32 v131, v27, v131
	v_mul_f32_e32 v131, v131, v15
	v_cvt_pk_bf16_f32 v139, v64, v131
	v_add_u32_e32 v64, 0xb0, v130
	v_mad_i64_i32 v[132:133], s[2:3], v64, s4, v[132:133]
	v_mul_f32_e32 v64, 0xbfb8aa3b, v20
	v_mul_f32_e32 v131, 0xbfb8aa3b, v21
	v_exp_f32_e32 v64, v64
	v_exp_f32_e32 v131, v131
	global_store_dwordx4 v[140:141], v[136:139], off sc1
	s_mov_b64 s[2:3], 0
	v_add_f32_e32 v64, 1.0, v64
	v_add_f32_e32 v131, 1.0, v131
	v_rcp_f32_e32 v64, v64
	v_rcp_f32_e32 v131, v131
	v_lshl_add_u64 v[136:137], v[132:133], 0, v[134:135]
	v_mul_f32_e32 v64, v20, v64
	v_mul_f32_e32 v131, v21, v131
	v_mul_f32_e32 v64, v64, v4
	v_mul_f32_e32 v131, v131, v5
	v_cvt_pk_bf16_f32 v132, v64, v131
	v_mul_f32_e32 v64, 0xbfb8aa3b, v22
	v_mul_f32_e32 v131, 0xbfb8aa3b, v23
	v_exp_f32_e32 v64, v64
	v_exp_f32_e32 v131, v131
	v_add_f32_e32 v64, 1.0, v64
	v_add_f32_e32 v131, 1.0, v131
	v_rcp_f32_e32 v64, v64
	v_rcp_f32_e32 v131, v131
	v_mul_f32_e32 v64, v22, v64
	v_mul_f32_e32 v131, v23, v131
	v_mul_f32_e32 v64, v64, v6
	v_mul_f32_e32 v131, v131, v7
	v_cvt_pk_bf16_f32 v133, v64, v131
	v_mul_f32_e32 v64, 0xbfb8aa3b, v8
	v_mul_f32_e32 v131, 0xbfb8aa3b, v9
	v_exp_f32_e32 v64, v64
	v_exp_f32_e32 v131, v131
	v_add_f32_e32 v64, 1.0, v64
	v_add_f32_e32 v131, 1.0, v131
	v_rcp_f32_e32 v64, v64
	v_rcp_f32_e32 v131, v131
	v_mul_f32_e32 v64, v8, v64
	v_mul_f32_e32 v131, v9, v131
	v_mul_f32_e32 v64, v64, v0
	v_mul_f32_e32 v131, v131, v1
	v_cvt_pk_bf16_f32 v134, v64, v131
	v_mul_f32_e32 v64, 0xbfb8aa3b, v10
	v_mul_f32_e32 v131, 0xbfb8aa3b, v11
	v_exp_f32_e32 v64, v64
	v_exp_f32_e32 v131, v131
	v_add_f32_e32 v64, 1.0, v64
	v_add_f32_e32 v131, 1.0, v131
	v_rcp_f32_e32 v64, v64
	v_rcp_f32_e32 v131, v131
	v_mul_f32_e32 v64, v10, v64
	v_mul_f32_e32 v131, v11, v131
	v_mul_f32_e32 v64, v64, v2
	v_mul_f32_e32 v131, v131, v3
	v_cvt_pk_bf16_f32 v135, v64, v131
	global_store_dwordx4 v[136:137], v[132:135], off sc1
.LBB0_589:
	s_andn2_b64 vcc, exec, s[2:3]
	s_cbranch_vccnz .LBB0_591
	v_lshl_or_b32 v132, s83, 8, v203
	v_ashrrev_i32_e32 v131, 31, v130
	v_ashrrev_i32_e32 v133, 31, v132
	v_lshlrev_b64 v[134:135], 13, v[130:131]
	v_lshl_add_u64 v[136:137], s[28:29], 0, v[134:135]
	v_lshlrev_b64 v[132:133], 2, v[132:133]
	v_lshl_add_u64 v[148:149], v[136:137], 0, v[132:133]
	global_load_dwordx4 v[136:139], v[148:149], off
	global_load_dwordx4 v[140:143], v[148:149], off offset:64
	global_load_dwordx4 v[144:147], v[148:149], off offset:512
	s_nop 0
	global_load_dwordx4 v[148:151], v[148:149], off offset:576
	v_or_b32_e32 v152, 16, v130
	v_ashrrev_i32_e32 v153, 31, v152
	v_lshlrev_b64 v[160:161], 13, v[152:153]
	v_lshl_add_u64 v[152:153], s[28:29], 0, v[160:161]
	v_lshl_add_u64 v[182:183], v[152:153], 0, v[132:133]
	global_load_dwordx4 v[152:155], v[182:183], off offset:576
	global_load_dwordx4 v[156:159], v[182:183], off offset:512
	global_load_dwordx4 v[178:181], v[182:183], off offset:64
	s_nop 0
	global_load_dwordx4 v[182:185], v[182:183], off
	s_mov_b64 s[2:3], 0x100000
	s_waitcnt vmcnt(0)
	v_pk_fma_f32 v[126:127], s[38:39], v[126:127], v[136:137]
	v_lshl_add_u64 v[136:137], s[10:11], 0, v[134:135]
	v_lshl_add_u64 v[136:137], v[136:137], 0, v[132:133]
	v_pk_fma_f32 v[116:117], s[48:49], v[116:117], v[150:151]
	v_pk_fma_f32 v[114:115], s[38:39], v[114:115], v[148:149]
	global_store_dwordx4 v[136:137], v[114:117], off offset:576 sc1
	v_pk_fma_f32 v[128:129], s[48:49], v[128:129], v[138:139]
	v_pk_fma_f32 v[124:125], s[48:49], v[124:125], v[142:143]
	v_or_b32_e32 v114, 32, v130
	v_pk_fma_f32 v[122:123], s[38:39], v[122:123], v[140:141]
	v_pk_fma_f32 v[120:121], s[48:49], v[120:121], v[146:147]
	v_pk_fma_f32 v[118:119], s[38:39], v[118:119], v[144:145]
	v_ashrrev_i32_e32 v115, 31, v114
	global_store_dwordx4 v[136:137], v[126:129], off sc1
	global_store_dwordx4 v[136:137], v[122:125], off offset:64 sc1
	global_store_dwordx4 v[136:137], v[118:121], off offset:512 sc1
	v_lshlrev_b64 v[136:137], 13, v[114:115]
	v_lshl_add_u64 v[114:115], s[28:29], 0, v[136:137]
	v_lshl_add_u64 v[138:139], s[10:11], 0, v[160:161]
	v_lshl_add_u64 v[126:127], v[114:115], 0, v[132:133]
	v_lshl_add_u64 v[138:139], v[138:139], 0, v[132:133]
	v_pk_fma_f32 v[100:101], s[48:49], v[100:101], v[154:155]
	v_pk_fma_f32 v[98:99], s[38:39], v[98:99], v[152:153]
	global_load_dwordx4 v[114:117], v[126:127], off offset:576
	global_load_dwordx4 v[118:121], v[126:127], off offset:512
	global_load_dwordx4 v[122:125], v[126:127], off offset:64
	s_nop 0
	global_load_dwordx4 v[126:129], v[126:127], off
	v_pk_fma_f32 v[112:113], s[48:49], v[112:113], v[184:185]
	global_store_dwordx4 v[138:139], v[98:101], off offset:576 sc1
	v_pk_fma_f32 v[110:111], s[38:39], v[110:111], v[182:183]
	global_store_dwordx4 v[138:139], v[110:113], off sc1
	v_or_b32_e32 v98, 48, v130
	v_ashrrev_i32_e32 v99, 31, v98
	v_lshlrev_b64 v[112:113], 13, v[98:99]
	v_pk_fma_f32 v[108:109], s[48:49], v[108:109], v[180:181]
	v_pk_fma_f32 v[106:107], s[38:39], v[106:107], v[178:179]
	v_pk_fma_f32 v[104:105], s[48:49], v[104:105], v[158:159]
	v_pk_fma_f32 v[102:103], s[38:39], v[102:103], v[156:157]
	v_lshl_add_u64 v[98:99], s[28:29], 0, v[112:113]
	global_store_dwordx4 v[138:139], v[106:109], off offset:64 sc1
	global_store_dwordx4 v[138:139], v[102:105], off offset:512 sc1
	v_lshl_add_u64 v[98:99], v[98:99], 0, v[132:133]
	global_load_dwordx4 v[100:103], v[98:99], off offset:576
	global_load_dwordx4 v[104:107], v[98:99], off offset:512
	global_load_dwordx4 v[108:111], v[98:99], off offset:64
	global_load_dwordx4 v[138:141], v[98:99], off
	v_lshl_add_u64 v[98:99], s[10:11], 0, v[136:137]
	v_lshl_add_u64 v[98:99], v[98:99], 0, v[132:133]
	v_lshl_add_u64 v[112:113], s[10:11], 0, v[112:113]
	v_lshl_add_u64 v[112:113], v[112:113], 0, v[132:133]
	s_waitcnt vmcnt(11)
;     __device__ __forceinline__ void operator()(const f32x4 (&acc)[2][2][4][2], const pg8::Unit& u, int wr, int wc, int fr, int fq) const {
;     ...
; #pragma unroll
;         for (int g = 0; g < 8; ++g) {
;             const int ai = g >> 2, m = g & 3;
;             if (g < 7) { const int ai2 = (g + 1) >> 2, m2 = (g + 1) & 3; const size_t off2 = (size_t)(row0 + ai2 * 128 + m2 * 16) * D_ + col0;
; #pragma unroll
;                 for (int j = 0; j < 4; ++j) nxt[j] = *(const f32x4*)(res + off2 + (j >> 1) * 128 + (j & 1) * 16); }
;             const size_t off = (size_t)(row0 + ai * 128 + m * 16) * D_ + col0;
; #pragma unroll
;             for (int j = 0; j < 4; ++j) *(f32x4*)(out + off + (j >> 1) * 128 + (j & 1) * 16) = cur[j] + scale * acc[ai][j >> 1][m][j & 1];
; #pragma unroll
;             for (int j = 0; j < 4; ++j) cur[j] = nxt[j];
;         }
	v_pk_fma_f32 v[80:81], s[48:49], v[80:81], v[116:117]
	s_waitcnt vmcnt(10)
	v_pk_fma_f32 v[88:89], s[48:49], v[88:89], v[120:121]
	s_waitcnt vmcnt(9)
	v_pk_fma_f32 v[92:93], s[48:49], v[92:93], v[124:125]
	s_waitcnt vmcnt(8)
	v_pk_fma_f32 v[96:97], s[48:49], v[96:97], v[128:129]
	v_pk_fma_f32 v[94:95], s[38:39], v[94:95], v[126:127]
	v_pk_fma_f32 v[90:91], s[38:39], v[90:91], v[122:123]
	v_pk_fma_f32 v[86:87], s[38:39], v[86:87], v[118:119]
	v_pk_fma_f32 v[78:79], s[38:39], v[78:79], v[114:115]
	global_store_dwordx4 v[98:99], v[94:97], off sc1
	global_store_dwordx4 v[98:99], v[90:93], off offset:64 sc1
	global_store_dwordx4 v[98:99], v[86:89], off offset:512 sc1
	global_store_dwordx4 v[98:99], v[78:81], off offset:576 sc1
	v_lshl_add_u64 v[98:99], v[134:135], 0, s[2:3]
	s_waitcnt vmcnt(7)
	v_pk_fma_f32 v[68:69], s[48:49], v[68:69], v[102:103]
	v_lshl_add_u64 v[78:79], s[28:29], 0, v[98:99]
	v_lshl_add_u64 v[94:95], v[78:79], 0, v[132:133]
	v_pk_fma_f32 v[66:67], s[38:39], v[66:67], v[100:101]
	global_load_dwordx4 v[78:81], v[94:95], off offset:576
	global_load_dwordx4 v[86:89], v[94:95], off offset:512
	global_load_dwordx4 v[90:93], v[94:95], off offset:64
	s_nop 0
	global_load_dwordx4 v[94:97], v[94:95], off
	s_waitcnt vmcnt(8)
	v_pk_fma_f32 v[84:85], s[48:49], v[84:85], v[140:141]
	global_store_dwordx4 v[112:113], v[66:69], off offset:576 sc1
	v_pk_fma_f32 v[82:83], s[38:39], v[82:83], v[138:139]
	global_store_dwordx4 v[112:113], v[82:85], off sc1
	v_add_u32_e32 v66, 0x90, v130
	v_ashrrev_i32_e32 v67, 31, v66
	v_lshlrev_b64 v[82:83], 13, v[66:67]
	v_pk_fma_f32 v[76:77], s[48:49], v[76:77], v[110:111]
	v_pk_fma_f32 v[74:75], s[38:39], v[74:75], v[108:109]
	v_pk_fma_f32 v[72:73], s[48:49], v[72:73], v[106:107]
	v_pk_fma_f32 v[70:71], s[38:39], v[70:71], v[104:105]
	v_lshl_add_u64 v[66:67], s[28:29], 0, v[82:83]
	global_store_dwordx4 v[112:113], v[74:77], off offset:64 sc1
	global_store_dwordx4 v[112:113], v[70:73], off offset:512 sc1
	v_lshl_add_u64 v[84:85], v[66:67], 0, v[132:133]
	global_load_dwordx4 v[66:69], v[84:85], off offset:576
	global_load_dwordx4 v[70:73], v[84:85], off offset:512
	global_load_dwordx4 v[74:77], v[84:85], off offset:64
	global_load_dwordx4 v[100:103], v[84:85], off
	v_lshl_add_u64 v[84:85], s[10:11], 0, v[98:99]
	v_lshl_add_u64 v[84:85], v[84:85], 0, v[132:133]
	s_waitcnt vmcnt(11)
	v_pk_fma_f32 v[50:51], s[48:49], v[50:51], v[80:81]
	v_pk_fma_f32 v[48:49], s[38:39], v[48:49], v[78:79]
	global_store_dwordx4 v[84:85], v[48:51], off offset:576 sc1
	s_waitcnt vmcnt(9)
	v_pk_fma_f32 v[62:63], s[48:49], v[62:63], v[96:97]
	v_pk_fma_f32 v[60:61], s[38:39], v[60:61], v[94:95]
	v_add_u32_e32 v48, 0xa0, v130
	v_ashrrev_i32_e32 v49, 31, v48
	v_lshlrev_b64 v[78:79], 13, v[48:49]
	v_pk_fma_f32 v[58:59], s[48:49], v[58:59], v[92:93]
	v_pk_fma_f32 v[56:57], s[38:39], v[56:57], v[90:91]
	v_pk_fma_f32 v[54:55], s[48:49], v[54:55], v[88:89]
	v_pk_fma_f32 v[52:53], s[38:39], v[52:53], v[86:87]
	v_lshl_add_u64 v[48:49], s[28:29], 0, v[78:79]
	v_lshl_add_u64 v[80:81], s[10:11], 0, v[82:83]
	global_store_dwordx4 v[84:85], v[60:63], off sc1
	global_store_dwordx4 v[84:85], v[56:59], off offset:64 sc1
	global_store_dwordx4 v[84:85], v[52:55], off offset:512 sc1
	v_lshl_add_u64 v[60:61], v[48:49], 0, v[132:133]
	v_lshl_add_u64 v[80:81], v[80:81], 0, v[132:133]
	s_waitcnt vmcnt(7)
	v_pk_fma_f32 v[34:35], s[48:49], v[34:35], v[68:69]
	v_pk_fma_f32 v[32:33], s[38:39], v[32:33], v[66:67]
	global_load_dwordx4 v[52:55], v[60:61], off offset:512
	global_load_dwordx4 v[48:51], v[60:61], off offset:576
	global_load_dwordx4 v[56:59], v[60:61], off offset:64
	s_nop 0
	global_load_dwordx4 v[60:63], v[60:61], off
	s_waitcnt vmcnt(8)
	v_pk_fma_f32 v[46:47], s[48:49], v[46:47], v[102:103]
	global_store_dwordx4 v[80:81], v[32:35], off offset:576 sc1
	v_pk_fma_f32 v[44:45], s[38:39], v[44:45], v[100:101]
	v_pk_fma_f32 v[42:43], s[48:49], v[42:43], v[76:77]
	v_add_u32_e32 v32, 0xb0, v130
	v_ashrrev_i32_e32 v33, 31, v32
	v_lshlrev_b64 v[32:33], 13, v[32:33]
	v_pk_fma_f32 v[40:41], s[38:39], v[40:41], v[74:75]
	v_pk_fma_f32 v[38:39], s[48:49], v[38:39], v[72:73]
	v_pk_fma_f32 v[36:37], s[38:39], v[36:37], v[70:71]
	v_lshl_add_u64 v[34:35], s[28:29], 0, v[32:33]
	global_store_dwordx4 v[80:81], v[44:47], off sc1
	global_store_dwordx4 v[80:81], v[40:43], off offset:64 sc1
	global_store_dwordx4 v[80:81], v[36:39], off offset:512 sc1
	v_lshl_add_u64 v[46:47], v[34:35], 0, v[132:133]
	global_load_dwordx4 v[34:37], v[46:47], off
	global_load_dwordx4 v[38:41], v[46:47], off offset:64
	global_load_dwordx4 v[42:45], v[46:47], off offset:512
	global_load_dwordx4 v[66:69], v[46:47], off offset:576
	v_lshl_add_u64 v[46:47], s[10:11], 0, v[78:79]
	v_lshl_add_u64 v[46:47], v[46:47], 0, v[132:133]
	s_waitcnt vmcnt(11)
	v_pk_fma_f32 v[18:19], s[48:49], v[18:19], v[54:55]
	v_pk_fma_f32 v[16:17], s[38:39], v[16:17], v[52:53]
	global_store_dwordx4 v[46:47], v[16:19], off offset:512 sc1
	s_waitcnt vmcnt(11)
	v_pk_fma_f32 v[14:15], s[48:49], v[14:15], v[50:51]
	v_pk_fma_f32 v[12:13], s[38:39], v[12:13], v[48:49]
	v_lshl_add_u64 v[16:17], s[10:11], 0, v[32:33]
	s_waitcnt vmcnt(9)
	v_pk_fma_f32 v[30:31], s[48:49], v[30:31], v[62:63]
	v_pk_fma_f32 v[28:29], s[38:39], v[28:29], v[60:61]
	v_pk_fma_f32 v[26:27], s[48:49], v[26:27], v[58:59]
	v_pk_fma_f32 v[24:25], s[38:39], v[24:25], v[56:57]
	global_store_dwordx4 v[46:47], v[12:15], off offset:576 sc1
	v_lshl_add_u64 v[16:17], v[16:17], 0, v[132:133]
	global_store_dwordx4 v[46:47], v[28:31], off sc1
	global_store_dwordx4 v[46:47], v[24:27], off offset:64 sc1
	s_waitcnt vmcnt(7)
	v_pk_fma_f32 v[14:15], s[48:49], v[22:23], v[36:37]
	v_pk_fma_f32 v[12:13], s[38:39], v[20:21], v[34:35]
	s_waitcnt vmcnt(6)
	v_pk_fma_f32 v[10:11], s[48:49], v[10:11], v[40:41]
	v_pk_fma_f32 v[8:9], s[38:39], v[8:9], v[38:39]
	s_waitcnt vmcnt(5)
	v_pk_fma_f32 v[6:7], s[48:49], v[6:7], v[44:45]
	v_pk_fma_f32 v[4:5], s[38:39], v[4:5], v[42:43]
	s_waitcnt vmcnt(4)
	v_pk_fma_f32 v[2:3], s[48:49], v[2:3], v[68:69]
	v_pk_fma_f32 v[0:1], s[38:39], v[0:1], v[66:67]
	global_store_dwordx4 v[16:17], v[12:15], off sc1
	global_store_dwordx4 v[16:17], v[8:11], off offset:64 sc1
	global_store_dwordx4 v[16:17], v[4:7], off offset:512 sc1
	global_store_dwordx4 v[16:17], v[0:3], off offset:576 sc1
